# sc1 (agent-scope write-through) on the gemm-out epilogue and final-norm output stores only
# speedup vs baseline: 1.0240x; 1.0028x over previous
.LBB0_1214:
	v_or_b32_e32 v38, v50, v246
	v_lshlrev_b64 v[6:7], 12, v[40:41]
	v_cmp_gt_i32_e32 vcc, s51, v38
	v_ashrrev_i32_e32 v39, 31, v38
	v_add_u32_e32 v40, 0xffffc000, v38
	v_cndmask_b32_e32 v39, 0, v39, vcc
	v_cndmask_b32_e32 v38, v40, v38, vcc
	v_cndmask_b32_e32 v41, v43, v5, vcc
	v_cndmask_b32_e32 v40, v42, v4, vcc
	v_lshlrev_b64 v[38:39], 12, v[38:39]
	v_lshl_add_u64 v[6:7], v[44:45], 0, v[6:7]
	v_lshl_add_u64 v[38:39], v[40:41], 0, v[38:39]
	v_lshl_add_u64 v[6:7], v[6:7], 0, v[48:49]
	v_lshl_add_u64 v[44:45], v[38:39], 0, v[48:49]
	ds_read_b128 v[38:41], v254 offset:8704
	global_load_dwordx4 v[6:9], v[6:7], off nt
	s_mov_b32 s6, 0
	s_waitcnt vmcnt(7) lgkmcnt(0)
	v_pk_fma_f32 v[14:15], v[0:1], v[38:39], v[14:15]
	v_pk_fma_f32 v[16:17], v[2:3], v[40:41], v[16:17]
	global_store_dwordx4 v[44:45], v[14:17], off sc1
	s_nop 1
	v_or_b32_e32 v14, v50, v247
	v_cmp_gt_i32_e32 vcc, s51, v14
	v_ashrrev_i32_e32 v15, 31, v14
	v_add_u32_e32 v16, 0xffffc000, v14
	v_cndmask_b32_e32 v15, 0, v15, vcc
	v_cndmask_b32_e32 v14, v16, v14, vcc
	v_cndmask_b32_e32 v17, v43, v5, vcc
	v_cndmask_b32_e32 v16, v42, v4, vcc
	v_lshlrev_b64 v[14:15], 12, v[14:15]
	v_lshl_add_u64 v[14:15], v[16:17], 0, v[14:15]
	v_lshl_add_u64 v[38:39], v[14:15], 0, v[48:49]
	ds_read_b128 v[14:17], v254 offset:9792
	s_waitcnt vmcnt(7) lgkmcnt(0)
	v_pk_fma_f32 v[10:11], v[0:1], v[14:15], v[10:11]
	v_pk_fma_f32 v[12:13], v[2:3], v[16:17], v[12:13]
	global_store_dwordx4 v[38:39], v[10:13], off sc1
	s_nop 1
	v_or_b32_e32 v10, v50, v248
	v_cmp_gt_i32_e32 vcc, s51, v10
	v_ashrrev_i32_e32 v11, 31, v10
	v_add_u32_e32 v12, 0xffffc000, v10
	v_cndmask_b32_e32 v11, 0, v11, vcc
	v_cndmask_b32_e32 v10, v12, v10, vcc
	v_cndmask_b32_e32 v13, v43, v5, vcc
	v_cndmask_b32_e32 v12, v42, v4, vcc
	v_lshlrev_b64 v[10:11], 12, v[10:11]
	v_lshl_add_u64 v[10:11], v[12:13], 0, v[10:11]
	v_lshl_add_u64 v[14:15], v[10:11], 0, v[48:49]
	ds_read_b128 v[10:13], v254 offset:10880
	s_waitcnt vmcnt(7) lgkmcnt(0)
	v_pk_fma_f32 v[10:11], v[0:1], v[10:11], v[22:23]
	v_pk_fma_f32 v[12:13], v[2:3], v[12:13], v[24:25]
	global_store_dwordx4 v[14:15], v[10:13], off sc1
	s_nop 1
	v_or_b32_e32 v10, v50, v249
	v_cmp_gt_i32_e32 vcc, s51, v10
	v_ashrrev_i32_e32 v11, 31, v10
	v_add_u32_e32 v12, 0xffffc000, v10
	v_cndmask_b32_e32 v11, 0, v11, vcc
	v_cndmask_b32_e32 v10, v12, v10, vcc
	v_cndmask_b32_e32 v13, v43, v5, vcc
	v_cndmask_b32_e32 v12, v42, v4, vcc
	v_lshlrev_b64 v[10:11], 12, v[10:11]
	v_lshl_add_u64 v[10:11], v[12:13], 0, v[10:11]
	v_lshl_add_u64 v[14:15], v[10:11], 0, v[48:49]
	ds_read_b128 v[10:13], v254 offset:11968
	s_waitcnt vmcnt(7) lgkmcnt(0)
	v_pk_fma_f32 v[10:11], v[0:1], v[10:11], v[18:19]
	v_pk_fma_f32 v[12:13], v[2:3], v[12:13], v[20:21]
	global_store_dwordx4 v[14:15], v[10:13], off sc1
	s_nop 1
	v_or_b32_e32 v10, v50, v250
	v_cmp_gt_i32_e32 vcc, s51, v10
	v_ashrrev_i32_e32 v11, 31, v10
	v_add_u32_e32 v12, 0xffffc000, v10
	v_cndmask_b32_e32 v11, 0, v11, vcc
	v_cndmask_b32_e32 v10, v12, v10, vcc
	v_cndmask_b32_e32 v13, v43, v5, vcc
	v_cndmask_b32_e32 v12, v42, v4, vcc
	v_lshlrev_b64 v[10:11], 12, v[10:11]
	v_lshl_add_u64 v[10:11], v[12:13], 0, v[10:11]
	v_lshl_add_u64 v[14:15], v[10:11], 0, v[48:49]
	ds_read_b128 v[10:13], v254 offset:13056
	s_waitcnt vmcnt(7) lgkmcnt(0)
	v_pk_fma_f32 v[10:11], v[0:1], v[10:11], v[30:31]
	v_pk_fma_f32 v[12:13], v[2:3], v[12:13], v[32:33]
	global_store_dwordx4 v[14:15], v[10:13], off sc1
	s_nop 1
	v_or_b32_e32 v10, v50, v251
	v_cmp_gt_i32_e32 vcc, s51, v10
	v_ashrrev_i32_e32 v11, 31, v10
	v_add_u32_e32 v12, 0xffffc000, v10
	v_cndmask_b32_e32 v11, 0, v11, vcc
	v_cndmask_b32_e32 v10, v12, v10, vcc
	v_cndmask_b32_e32 v13, v43, v5, vcc
	v_cndmask_b32_e32 v12, v42, v4, vcc
	v_lshlrev_b64 v[10:11], 12, v[10:11]
	v_lshl_add_u64 v[10:11], v[12:13], 0, v[10:11]
	v_lshl_add_u64 v[14:15], v[10:11], 0, v[48:49]
	ds_read_b128 v[10:13], v254 offset:14144
	s_waitcnt vmcnt(7) lgkmcnt(0)
	v_pk_fma_f32 v[10:11], v[0:1], v[10:11], v[26:27]
	v_pk_fma_f32 v[12:13], v[2:3], v[12:13], v[28:29]
	global_store_dwordx4 v[14:15], v[10:13], off sc1
	s_nop 1
	v_or_b32_e32 v10, v50, v252
	v_cmp_gt_i32_e32 vcc, s51, v10
	v_ashrrev_i32_e32 v11, 31, v10
	v_add_u32_e32 v12, 0xffffc000, v10
	v_cndmask_b32_e32 v11, 0, v11, vcc
	v_cndmask_b32_e32 v10, v12, v10, vcc
	v_cndmask_b32_e32 v13, v43, v5, vcc
	v_cndmask_b32_e32 v12, v42, v4, vcc
	v_lshlrev_b64 v[10:11], 12, v[10:11]
	v_lshl_add_u64 v[10:11], v[12:13], 0, v[10:11]
	v_lshl_add_u64 v[14:15], v[10:11], 0, v[48:49]
	ds_read_b128 v[10:13], v254 offset:15232
	s_waitcnt vmcnt(7) lgkmcnt(0)
	v_pk_fma_f32 v[10:11], v[0:1], v[10:11], v[34:35]
	v_pk_fma_f32 v[12:13], v[2:3], v[12:13], v[36:37]
	global_store_dwordx4 v[14:15], v[10:13], off sc1
	s_nop 1
	v_or_b32_e32 v10, v50, v253
	v_cmp_gt_i32_e32 vcc, s51, v10
	v_ashrrev_i32_e32 v11, 31, v10
	v_add_u32_e32 v12, 0xffffc000, v10
	v_cndmask_b32_e32 v11, 0, v11, vcc
	v_cndmask_b32_e32 v10, v12, v10, vcc
	v_cndmask_b32_e32 v5, v43, v5, vcc
	v_cndmask_b32_e32 v4, v42, v4, vcc
	v_lshlrev_b64 v[10:11], 12, v[10:11]
	v_lshl_add_u64 v[4:5], v[4:5], 0, v[10:11]
	ds_read_b128 v[10:13], v254 offset:16320
	v_lshl_add_u64 v[4:5], v[4:5], 0, v[48:49]
	s_waitcnt vmcnt(7) lgkmcnt(0)
	v_pk_fma_f32 v[0:1], v[0:1], v[10:11], v[6:7]
	v_pk_fma_f32 v[2:3], v[2:3], v[12:13], v[8:9]
	global_store_dwordx4 v[4:5], v[0:3], off sc1
	s_barrier

.LBB0_1336:
	v_add_u32_e32 v47, 0xffffc000, v46
	v_ashrrev_i32_e32 v51, 31, v46
	v_cndmask_b32_e64 v53, 0, v51, s[6:7]
	v_cndmask_b32_e64 v52, v47, v46, s[6:7]
	v_lshlrev_b64 v[34:35], 12, v[36:37]
	v_cndmask_b32_e64 v55, v43, v5, s[6:7]
	v_cndmask_b32_e64 v54, v42, v4, s[6:7]
	v_lshlrev_b64 v[52:53], 12, v[52:53]
	v_lshl_add_u64 v[34:35], v[48:49], 0, v[34:35]
	v_lshlrev_b64 v[48:49], 2, v[44:45]
	v_lshl_add_u64 v[52:53], v[54:55], 0, v[52:53]
	v_lshl_add_u64 v[56:57], v[52:53], 0, v[48:49]
	ds_read_b128 v[52:55], v254
	v_lshl_add_u64 v[34:35], v[34:35], 0, v[48:49]
	global_load_dwordx4 v[34:37], v[34:35], off nt
	s_mov_b64 s[6:7], -1
	s_waitcnt vmcnt(7) lgkmcnt(0)
	v_pk_fma_f32 v[14:15], v[0:1], v[52:53], v[14:15]
	v_pk_fma_f32 v[16:17], v[2:3], v[54:55], v[16:17]
	global_store_dwordx4 v[56:57], v[14:17], off sc1
	s_nop 1
	v_or_b32_e32 v14, v50, v239
	v_cmp_gt_i32_e32 vcc, s51, v14
	v_ashrrev_i32_e32 v15, 31, v14
	v_add_u32_e32 v16, 0xffffc000, v14
	v_cndmask_b32_e32 v15, 0, v15, vcc
	v_cndmask_b32_e32 v14, v16, v14, vcc
	v_cndmask_b32_e32 v17, v43, v5, vcc
	v_cndmask_b32_e32 v16, v42, v4, vcc
	v_lshlrev_b64 v[14:15], 12, v[14:15]
	v_lshl_add_u64 v[14:15], v[16:17], 0, v[14:15]
	v_lshl_add_u64 v[52:53], v[14:15], 0, v[48:49]
	ds_read_b128 v[14:17], v254 offset:1088
	s_waitcnt vmcnt(7) lgkmcnt(0)
	v_pk_fma_f32 v[10:11], v[0:1], v[14:15], v[10:11]
	v_pk_fma_f32 v[12:13], v[2:3], v[16:17], v[12:13]
	global_store_dwordx4 v[52:53], v[10:13], off sc1
	s_nop 1
	v_or_b32_e32 v10, v50, v240
	v_cmp_gt_i32_e32 vcc, s51, v10
	v_ashrrev_i32_e32 v11, 31, v10
	v_add_u32_e32 v12, 0xffffc000, v10
	v_cndmask_b32_e32 v11, 0, v11, vcc
	v_cndmask_b32_e32 v10, v12, v10, vcc
	v_cndmask_b32_e32 v13, v43, v5, vcc
	v_cndmask_b32_e32 v12, v42, v4, vcc
	v_lshlrev_b64 v[10:11], 12, v[10:11]
	v_lshl_add_u64 v[10:11], v[12:13], 0, v[10:11]
	v_lshl_add_u64 v[14:15], v[10:11], 0, v[48:49]
	ds_read_b128 v[10:13], v254 offset:2176
	s_waitcnt vmcnt(7) lgkmcnt(0)
	v_pk_fma_f32 v[10:11], v[0:1], v[10:11], v[22:23]
	v_pk_fma_f32 v[12:13], v[2:3], v[12:13], v[24:25]
	global_store_dwordx4 v[14:15], v[10:13], off sc1
	s_nop 1
	v_or_b32_e32 v10, v50, v241
	v_cmp_gt_i32_e32 vcc, s51, v10
	v_ashrrev_i32_e32 v11, 31, v10
	v_add_u32_e32 v12, 0xffffc000, v10
	v_cndmask_b32_e32 v11, 0, v11, vcc
	v_cndmask_b32_e32 v10, v12, v10, vcc
	v_cndmask_b32_e32 v13, v43, v5, vcc
	v_cndmask_b32_e32 v12, v42, v4, vcc
	v_lshlrev_b64 v[10:11], 12, v[10:11]
	v_lshl_add_u64 v[10:11], v[12:13], 0, v[10:11]
	v_lshl_add_u64 v[14:15], v[10:11], 0, v[48:49]
	ds_read_b128 v[10:13], v254 offset:3264
	s_waitcnt vmcnt(7) lgkmcnt(0)
	v_pk_fma_f32 v[10:11], v[0:1], v[10:11], v[18:19]
	v_pk_fma_f32 v[12:13], v[2:3], v[12:13], v[20:21]
	global_store_dwordx4 v[14:15], v[10:13], off sc1
	s_nop 1
	v_or_b32_e32 v10, v50, v242
	v_cmp_gt_i32_e32 vcc, s51, v10
	v_ashrrev_i32_e32 v11, 31, v10
	v_add_u32_e32 v12, 0xffffc000, v10
	v_cndmask_b32_e32 v11, 0, v11, vcc
	v_cndmask_b32_e32 v10, v12, v10, vcc
	v_cndmask_b32_e32 v13, v43, v5, vcc
	v_cndmask_b32_e32 v12, v42, v4, vcc
	v_lshlrev_b64 v[10:11], 12, v[10:11]
	v_lshl_add_u64 v[10:11], v[12:13], 0, v[10:11]
	v_lshl_add_u64 v[14:15], v[10:11], 0, v[48:49]
	ds_read_b128 v[10:13], v254 offset:4352
	s_waitcnt vmcnt(7) lgkmcnt(0)
	v_pk_fma_f32 v[10:11], v[0:1], v[10:11], v[30:31]
	v_pk_fma_f32 v[12:13], v[2:3], v[12:13], v[32:33]
	global_store_dwordx4 v[14:15], v[10:13], off sc1
	s_nop 1
	v_or_b32_e32 v10, v50, v243
	v_cmp_gt_i32_e32 vcc, s51, v10
	v_ashrrev_i32_e32 v11, 31, v10
	v_add_u32_e32 v12, 0xffffc000, v10
	v_cndmask_b32_e32 v11, 0, v11, vcc
	v_cndmask_b32_e32 v10, v12, v10, vcc
	v_cndmask_b32_e32 v13, v43, v5, vcc
	v_cndmask_b32_e32 v12, v42, v4, vcc
	v_lshlrev_b64 v[10:11], 12, v[10:11]
	v_lshl_add_u64 v[10:11], v[12:13], 0, v[10:11]
	v_lshl_add_u64 v[14:15], v[10:11], 0, v[48:49]
	ds_read_b128 v[10:13], v254 offset:5440
	s_waitcnt vmcnt(7) lgkmcnt(0)
	v_pk_fma_f32 v[10:11], v[0:1], v[10:11], v[26:27]
	v_pk_fma_f32 v[12:13], v[2:3], v[12:13], v[28:29]
	global_store_dwordx4 v[14:15], v[10:13], off sc1
	s_nop 1
	v_or_b32_e32 v10, v50, v244
	v_cmp_gt_i32_e32 vcc, s51, v10
	v_ashrrev_i32_e32 v11, 31, v10
	v_add_u32_e32 v12, 0xffffc000, v10
	v_cndmask_b32_e32 v11, 0, v11, vcc
	v_cndmask_b32_e32 v10, v12, v10, vcc
	v_cndmask_b32_e32 v13, v43, v5, vcc
	v_cndmask_b32_e32 v12, v42, v4, vcc
	v_lshlrev_b64 v[10:11], 12, v[10:11]
	v_lshl_add_u64 v[10:11], v[12:13], 0, v[10:11]
	v_lshl_add_u64 v[14:15], v[10:11], 0, v[48:49]
	ds_read_b128 v[10:13], v254 offset:6528
	s_waitcnt vmcnt(7) lgkmcnt(0)
	v_pk_fma_f32 v[10:11], v[0:1], v[10:11], v[38:39]
	v_pk_fma_f32 v[12:13], v[2:3], v[12:13], v[40:41]
	global_store_dwordx4 v[14:15], v[10:13], off sc1
	s_nop 1
	v_or_b32_e32 v10, v50, v245
	v_cmp_gt_i32_e32 vcc, s51, v10
	v_ashrrev_i32_e32 v11, 31, v10
	v_add_u32_e32 v12, 0xffffc000, v10
	v_cndmask_b32_e32 v11, 0, v11, vcc
	v_cndmask_b32_e32 v10, v12, v10, vcc
	v_cndmask_b32_e32 v13, v43, v5, vcc
	v_cndmask_b32_e32 v12, v42, v4, vcc
	v_lshlrev_b64 v[10:11], 12, v[10:11]
	v_lshl_add_u64 v[10:11], v[12:13], 0, v[10:11]
	v_lshl_add_u64 v[14:15], v[10:11], 0, v[48:49]
	ds_read_b128 v[10:13], v254 offset:7616
	s_and_b64 vcc, exec, s[4:5]
	s_waitcnt vmcnt(7) lgkmcnt(0)
	v_pk_fma_f32 v[10:11], v[0:1], v[10:11], v[34:35]
	v_pk_fma_f32 v[12:13], v[2:3], v[12:13], v[36:37]
	global_store_dwordx4 v[14:15], v[10:13], off sc1
	s_nop 1
	v_or_b32_e32 v10, 32, v46
	v_cmp_lt_i32_e64 s[0:1], s50, v10
	s_cbranch_vccnz .LBB0_1342
	s_and_saveexec_b64 s[6:7], s[0:1]
	s_xor_b64 s[6:7], exec, s[6:7]
	v_add_u32_e32 v128, 0xffffc020, v46
	v_mov_b64_e32 v[12:13], v[128:129]
	s_or_saveexec_b64 s[6:7], s[6:7]
	v_mov_b64_e32 v[14:15], v[42:43]
	s_xor_b64 exec, exec, s[6:7]
	v_ashrrev_i32_e32 v11, 31, v10
	v_mov_b64_e32 v[14:15], v[4:5]
	v_mov_b64_e32 v[12:13], v[10:11]
	s_or_b64 exec, exec, s[6:7]
	s_mov_b64 s[6:7], 0
